# MoBA attention unit: tile-0 K/V loads issued at unit start (before the q loads) instead of right before their wait
# speedup vs baseline: 1.0095x; 1.0046x over previous
; __device__ __forceinline__ float bf2f(unsigned short v) { return __uint_as_float(((unsigned)v) << 16); }
; template <int DQK, bool MOBA>
; __device__ __forceinline__ void attn_unit(const Args& A, int b, int h, int qb, lptr lds) {
;     ...
;     int tid_o = threadIdx.x; asm volatile("" : "+v"(tid_o));
;     const int tid = tid_o, lane = tid & 63, r32 = lane & 31, hi = lane >> 5;
;     const int wid = __builtin_amdgcn_readfirstlane(tid >> 6);
;     const int tb = b * SEQ, q0 = qb * 256, own = qb, bh = b * NH + h;
;     const int qrow = tb + q0 + wid * 32 + r32;
;     const int qrel = wid * 32 + r32;
;     __syncthreads();
;     bf16x8 qf[NS];
;     {
;         const bf16* qp = A.Q + (size_t)qrow * A.q_pitch + h * DQK + 8 * hi;
; #pragma unroll
;         for (int s = 0; s < NS; ++s) qf[s] = *(const bf16x8*)(qp + 16 * s);
;     }
;     {
;         float ssn = 0.f;
; #pragma unroll
;         for (int s = 0; s < 8; ++s)
; #pragma unroll
;             for (int e = 0; e < 8; ++e) { const float f = bf2f((unsigned short)qf[s][e]); ssn += f * f; }
;         ssn += __shfl_xor(ssn, 32);
.LBB0_761:
	s_lshl_b32 s0, s53, 2
	s_add_i32 s0, s0, s50
	s_ashr_i32 s1, s0, 31
	s_lshr_b32 s4, s1, 29
	s_add_i32 s4, s0, s4
	s_and_b32 s5, s4, -8
	v_mov_b32_e32 v162, v202
	s_sub_i32 s19, s0, s5
	s_lshl_b32 s4, s4, 8
	v_readfirstlane_b32 s5, v162
	s_and_b32 s70, s4, 0xfffff800
	s_lshl_b32 s17, s18, 8
	s_ashr_i32 s71, s5, 1
	s_add_i32 s42, s17, s70
	s_andn2_b32 s71, s71, 31
	v_and_b32_e32 v83, 31, v162
	s_add_i32 s4, s71, s42
	v_or_b32_e32 v160, s4, v83
	v_mov_b32_e32 v188, 0x20000
	ds_read_b32 v186, v188 offset:84
	v_mov_b32_e32 v187, 0
	s_waitcnt lgkmcnt(0)
	v_lshl_add_u64 v[0:1], s[88:89], 0, v[186:187]
	s_movk_i32 s4, 0x1800
	s_lshl_b32 s46, s19, 7
	v_and_b32_e32 v3, 64, v206
	v_bfe_u32 v82, v162, 5, 1
	v_mad_i64_i32 v[0:1], s[4:5], v160, s4, v[0:1]
	s_ashr_i32 s47, s46, 31
	v_xor_b32_e32 v2, 32, v206
	v_add_u32_e32 v89, 64, v3
	v_lshl_add_u64 v[0:1], s[46:47], 1, v[0:1]
	v_lshlrev_b32_e32 v36, 4, v82
	v_mov_b32_e32 v37, v181
	v_cmp_lt_i32_e32 vcc, v2, v89
	v_lshl_add_u64 v[0:1], v[0:1], 0, v[36:37]
	v_and_b32_e32 v37, 32, v162
	v_cndmask_b32_e32 v2, v206, v2, vcc
	s_barrier
	v_mov_b32_e32 v230, 0x14a00
	v_mov_b32_e32 v229, 0x40000000
	ds_write_b32 v230, v209
	v_lshrrev_b32_e32 v210, 4, v162
	v_add_u32_e32 v211, s42, v210
	v_mov_b32_e32 v214, 0x1800
	v_mad_u64_u32 v[212:213], vcc, v211, v214, 0
	v_and_b32_e32 v215, 15, v162
	v_lshlrev_b32_e32 v215, 4, v215
	v_lshl_add_u32 v215, s46, 1, v215
	v_add_co_u32_e32 v212, vcc, v212, v215
	v_mov_b32_e32 v216, s8
	v_mov_b32_e32 v217, s10
	v_addc_co_u32_e32 v213, vcc, 0, v213, vcc
	v_add_co_u32_e32 v218, vcc, s95, v212
	s_nop 1
	v_addc_co_u32_e32 v219, vcc, v216, v213, vcc
	v_add_co_u32_e32 v220, vcc, 0x30000, v218
	s_nop 1
	v_addc_co_u32_e32 v221, vcc, 0, v219, vcc
	global_load_dwordx4 v[186:189], v[218:219], off
	global_load_dwordx4 v[190:193], v[220:221], off
	v_add_co_u32_e32 v218, vcc, s9, v212
	s_nop 1
	v_addc_co_u32_e32 v219, vcc, v217, v213, vcc
	v_add_co_u32_e32 v220, vcc, 0x30000, v218
	s_nop 1
	v_addc_co_u32_e32 v221, vcc, 0, v219, vcc
	global_load_dwordx4 v[194:197], v[218:219], off
	global_load_dwordx4 v[198:201], v[220:221], off
	global_load_dwordx4 v[44:47], v[0:1], off offset:224
	global_load_dwordx4 v[52:55], v[0:1], off offset:192
	global_load_dwordx4 v[60:63], v[0:1], off offset:160
	global_load_dwordx4 v[68:71], v[0:1], off offset:128
	global_load_dwordx4 v[76:79], v[0:1], off offset:96
	global_load_dwordx4 v[84:87], v[0:1], off offset:64
	v_lshlrev_b32_e32 v170, 2, v2
	global_load_dwordx4 v[28:31], v37, s[30:31] offset:16
	global_load_dwordx4 v[32:35], v37, s[30:31]
	global_load_dwordx4 v[90:93], v[0:1], off
	global_load_dwordx4 v[94:97], v[0:1], off offset:32
	global_load_dwordx4 v[20:23], v37, s[30:31] offset:80
	global_load_dwordx4 v[24:27], v37, s[30:31] offset:64
	global_load_dwordx4 v[12:15], v37, s[30:31] offset:144
	global_load_dwordx4 v[16:19], v37, s[30:31] offset:128
	global_load_dwordx4 v[4:7], v37, s[30:31] offset:208
	global_load_dwordx4 v[8:11], v37, s[30:31] offset:192
	global_load_dwordx4 v[0:3], v37, s[30:31] offset:256
	s_lshl_b64 s[0:1], s[0:1], 12
	s_add_u32 s0, s66, s0
	v_ashrrev_i32_e32 v163, 31, v162
	s_addc_u32 s1, s67, s1
	v_ashrrev_i32_e32 v161, 31, v160
	s_cmp_gt_u32 s18, 3
	s_waitcnt vmcnt(8)
	v_and_b32_e32 v175, 0xffff0000, v90
	v_lshlrev_b32_e32 v174, 16, v90
	v_and_b32_e32 v169, 0xffff0000, v91
	v_lshlrev_b32_e32 v168, 16, v91
	v_pk_mul_f32 v[90:91], v[174:175], v[174:175]
	v_pk_mul_f32 v[172:173], v[168:169], v[168:169]
	v_add_f32_e32 v88, v90, v91
	v_and_b32_e32 v167, 0xffff0000, v92
	v_lshlrev_b32_e32 v166, 16, v92
	v_add_f32_e32 v88, v172, v88
	v_and_b32_e32 v165, 0xffff0000, v93
	v_lshlrev_b32_e32 v164, 16, v93
	v_pk_mul_f32 v[92:93], v[166:167], v[166:167]
	v_add_f32_e32 v88, v173, v88
	v_add_f32_e32 v88, v92, v88
	v_pk_mul_f32 v[148:149], v[164:165], v[164:165]
	v_add_f32_e32 v88, v93, v88
	s_waitcnt vmcnt(7)
	v_and_b32_e32 v159, 0xffff0000, v94
	v_lshlrev_b32_e32 v158, 16, v94
	v_add_f32_e32 v88, v148, v88
	v_and_b32_e32 v157, 0xffff0000, v95
	v_lshlrev_b32_e32 v156, 16, v95
	v_pk_mul_f32 v[94:95], v[158:159], v[158:159]
	v_add_f32_e32 v88, v149, v88
	v_add_f32_e32 v88, v94, v88
	v_pk_mul_f32 v[146:147], v[156:157], v[156:157]
	v_add_f32_e32 v88, v95, v88
	v_and_b32_e32 v155, 0xffff0000, v96
	v_lshlrev_b32_e32 v154, 16, v96
	v_add_f32_e32 v88, v146, v88
	v_and_b32_e32 v153, 0xffff0000, v97
	v_lshlrev_b32_e32 v152, 16, v97
	v_pk_mul_f32 v[96:97], v[154:155], v[154:155]
	v_add_f32_e32 v88, v147, v88
	v_add_f32_e32 v88, v96, v88
	v_pk_mul_f32 v[144:145], v[152:153], v[152:153]
	v_add_f32_e32 v88, v97, v88
	v_and_b32_e32 v151, 0xffff0000, v84
	v_lshlrev_b32_e32 v150, 16, v84
	v_add_f32_e32 v88, v144, v88
	v_and_b32_e32 v141, 0xffff0000, v85
	v_lshlrev_b32_e32 v140, 16, v85
	v_pk_mul_f32 v[84:85], v[150:151], v[150:151]
	v_add_f32_e32 v88, v145, v88
	v_add_f32_e32 v84, v84, v88
	v_pk_mul_f32 v[142:143], v[140:141], v[140:141]
	v_add_f32_e32 v84, v85, v84
	v_and_b32_e32 v81, 0xffff0000, v86
	v_lshlrev_b32_e32 v80, 16, v86
	v_add_f32_e32 v84, v142, v84
	v_and_b32_e32 v39, 0xffff0000, v47
	v_lshlrev_b32_e32 v38, 16, v47
	v_and_b32_e32 v41, 0xffff0000, v46
	v_lshlrev_b32_e32 v40, 16, v46
	v_and_b32_e32 v47, 0xffff0000, v55
	v_lshlrev_b32_e32 v46, 16, v55
	v_and_b32_e32 v49, 0xffff0000, v54
	v_lshlrev_b32_e32 v48, 16, v54
	v_and_b32_e32 v55, 0xffff0000, v63
	v_lshlrev_b32_e32 v54, 16, v63
	v_and_b32_e32 v57, 0xffff0000, v62
	v_lshlrev_b32_e32 v56, 16, v62
	v_and_b32_e32 v63, 0xffff0000, v71
	v_lshlrev_b32_e32 v62, 16, v71
	v_and_b32_e32 v65, 0xffff0000, v70
	v_lshlrev_b32_e32 v64, 16, v70
	v_and_b32_e32 v71, 0xffff0000, v79
	v_lshlrev_b32_e32 v70, 16, v79
; __device__ __forceinline__ unsigned cvt_pk_bf16(float lo, float hi) { f32x2 v = {lo, hi}; bf16x2_t b = __builtin_convertvector(v, bf16x2_t); return __builtin_bit_cast(unsigned, b); }
; __device__ __forceinline__ float bf2f(unsigned short v) { return __uint_as_float(((unsigned)v) << 16); }
; template <int DQK, bool MOBA>
; __device__ __forceinline__ void attn_unit(const Args& A, int b, int h, int qb, lptr lds) {
;     ...
;         float ssn = 0.f;
; #pragma unroll
;         for (int s = 0; s < 8; ++s)
; #pragma unroll
;             for (int e = 0; e < 8; ++e) { const float f = bf2f((unsigned short)qf[s][e]); ssn += f * f; }
;         ssn += __shfl_xor(ssn, 32);
;         const float scn = __builtin_amdgcn_rsqf(ssn * (1.0f / 128.0f) + 1e-6f) * A.qscale;
; #pragma unroll
;         for (int s = 0; s < 8; ++s) {
;             const f32x4 g0 = *(const f32x4*)(A.gq_n + 16 * s + 8 * hi), g1 = *(const f32x4*)(A.gq_n + 16 * s + 8 * hi + 4);
;             u32x4 w;
;             w.x = cvt_pk_bf16(bf2f((unsigned short)qf[s][0]) * scn * g0[0], bf2f((unsigned short)qf[s][1]) * scn * g0[1]);
;             w.y = cvt_pk_bf16(bf2f((unsigned short)qf[s][2]) * scn * g0[2], bf2f((unsigned short)qf[s][3]) * scn * g0[3]);
;             w.z = cvt_pk_bf16(bf2f((unsigned short)qf[s][4]) * scn * g1[0], bf2f((unsigned short)qf[s][5]) * scn * g1[1]);
;             w.w = cvt_pk_bf16(bf2f((unsigned short)qf[s][6]) * scn * g1[2], bf2f((unsigned short)qf[s][7]) * scn * g1[3]);
;             qf[s] = __builtin_bit_cast(bf16x8, w);
;         }
;     ...
;         lut[tid] = A.lut[h * 1024 + tid]; lut[tid + 512] = A.lut[h * 1024 + tid + 512];
;         km[tid] = A.kmean[(size_t)bh * 1024 + tid]; km[tid + 512] = A.kmean[(size_t)bh * 1024 + tid + 512];
	v_and_b32_e32 v73, 0xffff0000, v78
	v_lshlrev_b32_e32 v72, 16, v78
	v_and_b32_e32 v79, 0xffff0000, v87
	v_lshlrev_b32_e32 v78, 16, v87
	v_pk_mul_f32 v[86:87], v[80:81], v[80:81]
	v_add_f32_e32 v84, v143, v84
	v_add_f32_e32 v84, v86, v84
	v_pk_mul_f32 v[138:139], v[78:79], v[78:79]
	v_add_f32_e32 v84, v87, v84
	v_and_b32_e32 v75, 0xffff0000, v77
	v_lshlrev_b32_e32 v74, 16, v77
	v_and_b32_e32 v77, 0xffff0000, v76
	v_lshlrev_b32_e32 v76, 16, v76
	v_add_f32_e32 v84, v138, v84
	v_pk_mul_f32 v[136:137], v[76:77], v[76:77]
	v_add_f32_e32 v84, v139, v84
	v_add_f32_e32 v84, v136, v84
	v_pk_mul_f32 v[134:135], v[74:75], v[74:75]
	v_add_f32_e32 v84, v137, v84
	v_add_f32_e32 v84, v134, v84
	v_pk_mul_f32 v[132:133], v[72:73], v[72:73]
	v_add_f32_e32 v84, v135, v84
	v_add_f32_e32 v84, v132, v84
	v_pk_mul_f32 v[130:131], v[70:71], v[70:71]
	v_add_f32_e32 v84, v133, v84
	v_and_b32_e32 v67, 0xffff0000, v69
	v_lshlrev_b32_e32 v66, 16, v69
	v_and_b32_e32 v69, 0xffff0000, v68
	v_lshlrev_b32_e32 v68, 16, v68
	v_add_f32_e32 v84, v130, v84
	v_pk_mul_f32 v[128:129], v[68:69], v[68:69]
	v_add_f32_e32 v84, v131, v84
	v_add_f32_e32 v84, v128, v84
	v_pk_mul_f32 v[126:127], v[66:67], v[66:67]
	v_add_f32_e32 v84, v129, v84
	v_add_f32_e32 v84, v126, v84
	v_pk_mul_f32 v[124:125], v[64:65], v[64:65]
	v_add_f32_e32 v84, v127, v84
	v_add_f32_e32 v84, v124, v84
	v_pk_mul_f32 v[122:123], v[62:63], v[62:63]
	v_add_f32_e32 v84, v125, v84
	v_and_b32_e32 v59, 0xffff0000, v61
	v_lshlrev_b32_e32 v58, 16, v61
	v_and_b32_e32 v61, 0xffff0000, v60
	v_lshlrev_b32_e32 v60, 16, v60
	v_add_f32_e32 v84, v122, v84
	v_pk_mul_f32 v[120:121], v[60:61], v[60:61]
	v_add_f32_e32 v84, v123, v84
	v_add_f32_e32 v84, v120, v84
	v_pk_mul_f32 v[118:119], v[58:59], v[58:59]
	v_add_f32_e32 v84, v121, v84
	v_add_f32_e32 v84, v118, v84
	v_pk_mul_f32 v[116:117], v[56:57], v[56:57]
	v_add_f32_e32 v84, v119, v84
	v_add_f32_e32 v84, v116, v84
	v_pk_mul_f32 v[114:115], v[54:55], v[54:55]
	v_add_f32_e32 v84, v117, v84
	v_and_b32_e32 v51, 0xffff0000, v53
	v_lshlrev_b32_e32 v50, 16, v53
	v_and_b32_e32 v53, 0xffff0000, v52
	v_lshlrev_b32_e32 v52, 16, v52
	v_add_f32_e32 v84, v114, v84
	v_pk_mul_f32 v[112:113], v[52:53], v[52:53]
	v_add_f32_e32 v84, v115, v84
	v_add_f32_e32 v84, v112, v84
	v_pk_mul_f32 v[110:111], v[50:51], v[50:51]
	v_add_f32_e32 v84, v113, v84
	v_add_f32_e32 v84, v110, v84
	v_pk_mul_f32 v[108:109], v[48:49], v[48:49]
	v_add_f32_e32 v84, v111, v84
	v_add_f32_e32 v84, v108, v84
	v_pk_mul_f32 v[106:107], v[46:47], v[46:47]
	v_add_f32_e32 v84, v109, v84
	v_and_b32_e32 v43, 0xffff0000, v45
	v_lshlrev_b32_e32 v42, 16, v45
	v_and_b32_e32 v45, 0xffff0000, v44
	v_lshlrev_b32_e32 v44, 16, v44
	v_add_f32_e32 v84, v106, v84
	v_pk_mul_f32 v[104:105], v[44:45], v[44:45]
	v_add_f32_e32 v84, v107, v84
	v_add_f32_e32 v84, v104, v84
	v_pk_mul_f32 v[102:103], v[42:43], v[42:43]
	v_add_f32_e32 v84, v105, v84
	v_add_f32_e32 v84, v102, v84
	v_pk_mul_f32 v[100:101], v[40:41], v[40:41]
	v_add_f32_e32 v84, v103, v84
	v_add_f32_e32 v84, v100, v84
	v_pk_mul_f32 v[98:99], v[38:39], v[38:39]
	v_add_f32_e32 v84, v101, v84
	v_add_f32_e32 v84, v98, v84
	v_add_f32_e32 v84, v99, v84
	ds_bpermute_b32 v85, v170, v84
	global_load_dwordx4 v[90:93], v37, s[30:31] offset:272
	global_load_dwordx4 v[94:97], v37, s[30:31] offset:336
	global_load_dwordx4 v[98:101], v37, s[30:31] offset:320
	global_load_dwordx4 v[102:105], v37, s[30:31] offset:400
	global_load_dwordx4 v[106:109], v37, s[30:31] offset:384
	global_load_dwordx4 v[142:145], v37, s[30:31] offset:464
	global_load_dwordx4 v[146:149], v37, s[30:31] offset:448
	s_waitcnt lgkmcnt(0)
	v_add_f32_e32 v84, v84, v85
	v_fmamk_f32 v84, v84, 0x3c000000, v204
	v_rsq_f32_e32 v84, v84
	s_nop 0
	v_mul_f32_e32 v88, 0x3e0293ee, v84
	v_pk_mul_f32 v[84:85], v[88:89], v[174:175] op_sel_hi:[0,1]
	v_pk_mul_f32 v[32:33], v[32:33], v[84:85]
	s_nop 0
	v_cvt_pk_bf16_f32 v112, v32, v33
	v_pk_mul_f32 v[32:33], v[88:89], v[168:169] op_sel_hi:[0,1]
	v_pk_mul_f32 v[32:33], v[34:35], v[32:33]
	s_nop 0
	v_cvt_pk_bf16_f32 v113, v32, v33
	v_pk_mul_f32 v[32:33], v[88:89], v[166:167] op_sel_hi:[0,1]
	v_pk_mul_f32 v[28:29], v[28:29], v[32:33]
	s_nop 0
	v_cvt_pk_bf16_f32 v114, v28, v29
	v_pk_mul_f32 v[28:29], v[88:89], v[164:165] op_sel_hi:[0,1]
	v_pk_mul_f32 v[28:29], v[30:31], v[28:29]
	s_nop 0
	v_cvt_pk_bf16_f32 v37, v28, v29
	v_pk_mul_f32 v[28:29], v[88:89], v[158:159] op_sel_hi:[0,1]
	s_waitcnt vmcnt(12)
	v_pk_mul_f32 v[24:25], v[24:25], v[28:29]
	v_lshrrev_b32_e32 v30, 16, v37
	v_cvt_pk_bf16_f32 v116, v24, v25
	v_pk_mul_f32 v[24:25], v[88:89], v[156:157] op_sel_hi:[0,1]
	v_pk_mul_f32 v[24:25], v[26:27], v[24:25]
	v_and_b32_e32 v29, 0xffff0000, v116
	v_cvt_pk_bf16_f32 v117, v24, v25
	v_pk_mul_f32 v[24:25], v[88:89], v[154:155] op_sel_hi:[0,1]
	v_pk_mul_f32 v[20:21], v[20:21], v[24:25]
	v_lshlrev_b32_e32 v28, 16, v116
	v_cvt_pk_bf16_f32 v118, v20, v21
	v_pk_mul_f32 v[20:21], v[88:89], v[152:153] op_sel_hi:[0,1]
	v_pk_mul_f32 v[20:21], v[22:23], v[20:21]
	v_and_b32_e32 v27, 0xffff0000, v118
	v_cvt_pk_bf16_f32 v84, v20, v21
	v_pk_mul_f32 v[20:21], v[88:89], v[150:151] op_sel_hi:[0,1]
	s_waitcnt vmcnt(10)
	v_pk_mul_f32 v[16:17], v[16:17], v[20:21]
	v_lshl_add_u64 v[20:21], v[162:163], 2, s[0:1]
	v_cvt_pk_bf16_f32 v120, v16, v17
	v_pk_mul_f32 v[16:17], v[88:89], v[140:141] op_sel_hi:[0,1]
	v_pk_mul_f32 v[16:17], v[18:19], v[16:17]
	v_lshl_add_u32 v18, s19, 10, v162
	v_cvt_pk_bf16_f32 v121, v16, v17
	v_pk_mul_f32 v[16:17], v[88:89], v[80:81] op_sel_hi:[0,1]
	v_pk_mul_f32 v[12:13], v[12:13], v[16:17]
	v_ashrrev_i32_e32 v19, 31, v18
	v_cvt_pk_bf16_f32 v122, v12, v13
	v_pk_mul_f32 v[12:13], v[88:89], v[78:79] op_sel_hi:[0,1]
	v_pk_mul_f32 v[12:13], v[14:15], v[12:13]
	v_lshl_add_u64 v[18:19], v[18:19], 2, s[62:63]
	v_cvt_pk_bf16_f32 v80, v12, v13
	v_pk_mul_f32 v[12:13], v[88:89], v[76:77] op_sel_hi:[0,1]
	s_waitcnt vmcnt(8)
; __device__ __forceinline__ unsigned cvt_pk_bf16(float lo, float hi) { f32x2 v = {lo, hi}; bf16x2_t b = __builtin_convertvector(v, bf16x2_t); return __builtin_bit_cast(unsigned, b); }
; __device__ __forceinline__ float bf2f(unsigned short v) { return __uint_as_float(((unsigned)v) << 16); }
; template <int DQK, bool MOBA>
; __device__ __forceinline__ void attn_unit(const Args& A, int b, int h, int qb, lptr lds) {
;     ...
;             w.x = cvt_pk_bf16(bf2f((unsigned short)qf[s][0]) * scn * g0[0], bf2f((unsigned short)qf[s][1]) * scn * g0[1]);
;             w.y = cvt_pk_bf16(bf2f((unsigned short)qf[s][2]) * scn * g0[2], bf2f((unsigned short)qf[s][3]) * scn * g0[3]);
;             w.z = cvt_pk_bf16(bf2f((unsigned short)qf[s][4]) * scn * g1[0], bf2f((unsigned short)qf[s][5]) * scn * g1[1]);
;             w.w = cvt_pk_bf16(bf2f((unsigned short)qf[s][6]) * scn * g1[2], bf2f((unsigned short)qf[s][7]) * scn * g1[3]);
;             qf[s] = __builtin_bit_cast(bf16x8, w);
;         }
;     ...
;         lut[tid] = A.lut[h * 1024 + tid]; lut[tid + 512] = A.lut[h * 1024 + tid + 512];
;         km[tid] = A.kmean[(size_t)bh * 1024 + tid]; km[tid + 512] = A.kmean[(size_t)bh * 1024 + tid + 512];
;         pq = A.pos[qrow];
;         __syncthreads();
;         if (own <= 3) sel = (1u << own) - 1u;
	v_pk_mul_f32 v[8:9], v[8:9], v[12:13]
	global_load_dword v23, v[18:19], off
	s_nop 0
	global_load_dword v18, v[18:19], off offset:2048
	s_nop 0
	global_load_dword v19, v[20:21], off
	s_nop 0
	global_load_dword v20, v[20:21], off offset:2048
	v_cvt_pk_bf16_f32 v124, v8, v9
	v_pk_mul_f32 v[8:9], v[88:89], v[74:75] op_sel_hi:[0,1]
	v_pk_mul_f32 v[8:9], v[10:11], v[8:9]
	v_lshrrev_b32_e32 v22, 16, v84
	v_cvt_pk_bf16_f32 v125, v8, v9
	v_pk_mul_f32 v[8:9], v[88:89], v[72:73] op_sel_hi:[0,1]
	v_pk_mul_f32 v[4:5], v[4:5], v[8:9]
	v_lshrrev_b32_e32 v16, 16, v80
	v_cvt_pk_bf16_f32 v126, v4, v5
	v_pk_mul_f32 v[4:5], v[88:89], v[70:71] op_sel_hi:[0,1]
	v_pk_mul_f32 v[4:5], v[6:7], v[4:5]
	s_mov_b64 s[0:1], -1
	v_cvt_pk_bf16_f32 v81, v4, v5
	v_pk_mul_f32 v[4:5], v[88:89], v[68:69] op_sel_hi:[0,1]
	s_waitcnt vmcnt(11)
	v_pk_mul_f32 v[0:1], v[0:1], v[4:5]
	v_lshrrev_b32_e32 v6, 16, v81
	v_cvt_pk_bf16_f32 v128, v0, v1
	v_pk_mul_f32 v[0:1], v[88:89], v[66:67] op_sel_hi:[0,1]
	v_pk_mul_f32 v[0:1], v[2:3], v[0:1]
	v_lshl_add_u64 v[2:3], v[160:161], 2, s[54:55]
	global_load_dword v171, v[2:3], off
	v_cvt_pk_bf16_f32 v129, v0, v1
	v_pk_mul_f32 v[0:1], v[88:89], v[64:65] op_sel_hi:[0,1]
	s_waitcnt vmcnt(11)
	v_pk_mul_f32 v[0:1], v[90:91], v[0:1]
	v_lshlrev_b32_e32 v15, 16, v37
	v_cvt_pk_bf16_f32 v130, v0, v1
	v_pk_mul_f32 v[0:1], v[88:89], v[62:63] op_sel_hi:[0,1]
	v_pk_mul_f32 v[0:1], v[92:93], v[0:1]
	v_lshlrev_b32_e32 v14, 16, v30
	v_cvt_pk_bf16_f32 v85, v0, v1
	v_pk_mul_f32 v[0:1], v[88:89], v[60:61] op_sel_hi:[0,1]
	s_waitcnt vmcnt(9)
	v_pk_mul_f32 v[0:1], v[98:99], v[0:1]
	v_lshrrev_b32_e32 v4, 16, v85
	v_cvt_pk_bf16_f32 v132, v0, v1
	v_pk_mul_f32 v[0:1], v[88:89], v[58:59] op_sel_hi:[0,1]
	v_pk_mul_f32 v[0:1], v[100:101], v[0:1]
	v_lshlrev_b32_e32 v13, 16, v84
	v_cvt_pk_bf16_f32 v133, v0, v1
	v_pk_mul_f32 v[0:1], v[88:89], v[56:57] op_sel_hi:[0,1]
	v_pk_mul_f32 v[0:1], v[94:95], v[0:1]
	v_lshlrev_b32_e32 v12, 16, v22
	v_cvt_pk_bf16_f32 v134, v0, v1
	v_pk_mul_f32 v[0:1], v[88:89], v[54:55] op_sel_hi:[0,1]
	v_pk_mul_f32 v[0:1], v[96:97], v[0:1]
	v_lshlrev_b32_e32 v11, 16, v80
	v_cvt_pk_bf16_f32 v86, v0, v1
	v_pk_mul_f32 v[0:1], v[88:89], v[52:53] op_sel_hi:[0,1]
	s_waitcnt vmcnt(7)
	v_pk_mul_f32 v[0:1], v[106:107], v[0:1]
	v_lshrrev_b32_e32 v17, 16, v86
	v_cvt_pk_bf16_f32 v136, v0, v1
	v_pk_mul_f32 v[0:1], v[88:89], v[50:51] op_sel_hi:[0,1]
	v_pk_mul_f32 v[0:1], v[108:109], v[0:1]
	v_lshlrev_b32_e32 v10, 16, v16
	v_cvt_pk_bf16_f32 v137, v0, v1
	v_pk_mul_f32 v[0:1], v[88:89], v[48:49] op_sel_hi:[0,1]
	v_pk_mul_f32 v[0:1], v[102:103], v[0:1]
	v_lshlrev_b32_e32 v9, 16, v81
	v_cvt_pk_bf16_f32 v138, v0, v1
	v_pk_mul_f32 v[0:1], v[88:89], v[46:47] op_sel_hi:[0,1]
	v_pk_mul_f32 v[0:1], v[104:105], v[0:1]
	v_lshlrev_b32_e32 v8, 16, v6
	v_cvt_pk_bf16_f32 v87, v0, v1
	v_pk_mul_f32 v[0:1], v[88:89], v[44:45] op_sel_hi:[0,1]
	s_waitcnt vmcnt(5)
	v_pk_mul_f32 v[0:1], v[146:147], v[0:1]
	v_lshrrev_b32_e32 v21, 16, v87
	v_cvt_pk_bf16_f32 v140, v0, v1
	v_pk_mul_f32 v[0:1], v[88:89], v[42:43] op_sel_hi:[0,1]
	v_pk_mul_f32 v[0:1], v[148:149], v[0:1]
	v_lshlrev_b32_e32 v7, 16, v85
	v_cvt_pk_bf16_f32 v141, v0, v1
	v_pk_mul_f32 v[0:1], v[88:89], v[40:41] op_sel_hi:[0,1]
	v_pk_mul_f32 v[0:1], v[142:143], v[0:1]
	v_lshlrev_b32_e32 v6, 16, v4
	v_cvt_pk_bf16_f32 v142, v0, v1
	v_pk_mul_f32 v[0:1], v[88:89], v[38:39] op_sel_hi:[0,1]
	v_pk_mul_f32 v[0:1], v[144:145], v[0:1]
	v_lshlrev_b32_e32 v5, 16, v86
	v_cvt_pk_bf16_f32 v88, v0, v1
	v_lshl_add_u32 v1, v162, 2, 0
	v_lshrrev_b32_e32 v0, 16, v88
	v_add_u32_e32 v2, 0x12a00, v1
	v_add_u32_e32 v1, 0x13a00, v1
	s_waitcnt vmcnt(3)
	ds_write2st64_b32 v2, v23, v18 offset1:8
	s_waitcnt vmcnt(1)
	ds_write2st64_b32 v1, v19, v20 offset1:8
	v_lshlrev_b32_e32 v4, 16, v17
	v_lshlrev_b32_e32 v3, 16, v87
	v_lshlrev_b32_e32 v2, 16, v21
	v_lshlrev_b32_e32 v1, 16, v88
	v_lshlrev_b32_e32 v0, 16, v0
	v_and_b32_e32 v17, 0xffff0000, v113
	v_lshlrev_b32_e32 v16, 16, v113
	v_and_b32_e32 v23, 0xffff0000, v112
	v_lshlrev_b32_e32 v22, 16, v112
	v_and_b32_e32 v21, 0xffff0000, v114
	v_lshlrev_b32_e32 v20, 16, v114
	v_and_b32_e32 v19, 0xffff0000, v117
	v_lshlrev_b32_e32 v18, 16, v117
	v_lshlrev_b32_e32 v26, 16, v118
	v_and_b32_e32 v25, 0xffff0000, v121
	v_lshlrev_b32_e32 v24, 16, v121
	v_and_b32_e32 v35, 0xffff0000, v120
	v_lshlrev_b32_e32 v34, 16, v120
	v_and_b32_e32 v33, 0xffff0000, v122
	v_lshlrev_b32_e32 v32, 16, v122
	v_and_b32_e32 v31, 0xffff0000, v125
	v_lshlrev_b32_e32 v30, 16, v125
	v_and_b32_e32 v43, 0xffff0000, v124
	v_lshlrev_b32_e32 v42, 16, v124
	v_and_b32_e32 v41, 0xffff0000, v126
	v_lshlrev_b32_e32 v40, 16, v126
	v_and_b32_e32 v39, 0xffff0000, v129
	v_lshlrev_b32_e32 v38, 16, v129
	v_and_b32_e32 v49, 0xffff0000, v128
	v_lshlrev_b32_e32 v48, 16, v128
	v_and_b32_e32 v47, 0xffff0000, v130
	v_lshlrev_b32_e32 v46, 16, v130
	v_and_b32_e32 v45, 0xffff0000, v133
	v_lshlrev_b32_e32 v44, 16, v133
	v_and_b32_e32 v55, 0xffff0000, v132
	v_lshlrev_b32_e32 v54, 16, v132
	v_and_b32_e32 v53, 0xffff0000, v134
	v_lshlrev_b32_e32 v52, 16, v134
	v_and_b32_e32 v51, 0xffff0000, v137
	v_lshlrev_b32_e32 v50, 16, v137
	v_and_b32_e32 v61, 0xffff0000, v136
	v_lshlrev_b32_e32 v60, 16, v136
	v_and_b32_e32 v59, 0xffff0000, v138
	v_lshlrev_b32_e32 v58, 16, v138
	v_and_b32_e32 v57, 0xffff0000, v141
	v_lshlrev_b32_e32 v56, 16, v141
	v_and_b32_e32 v65, 0xffff0000, v140
	v_lshlrev_b32_e32 v64, 16, v140
	v_and_b32_e32 v63, 0xffff0000, v142
	v_lshlrev_b32_e32 v62, 16, v142
	s_waitcnt lgkmcnt(0)
	s_barrier
	s_cbranch_scc0 .LBB0_769
; #define LAS __attribute__((address_space(3)))
; __device__ __forceinline__ float bf2f(unsigned short v) { return __uint_as_float(((unsigned)v) << 16); }
; template <int DQK, bool MOBA>
; __device__ __forceinline__ void attn_unit(const Args& A, int b, int h, int qb, lptr lds) {
;     ...
;             float g[7];
; #pragma unroll
;             for (int j = 0; j < 7; ++j) {
;                 float a = 0.f;
;                 if (j < own) {
; #pragma unroll
;                     for (int s = 0; s < NS; ++s) {
;                         const f32x4 k0 = *(const LAS f32x4*)(km + j * 128 + 16 * s + 8 * hi), k1 = *(const LAS f32x4*)(km + j * 128 + 16 * s + 8 * hi + 4);
;                         a += bf2f((unsigned short)qf[s][0]) * k0[0] + bf2f((unsigned short)qf[s][1]) * k0[1] + bf2f((unsigned short)qf[s][2]) * k0[2] + bf2f((unsigned short)qf[s][3]) * k0[3];
;                         a += bf2f((unsigned short)qf[s][4]) * k1[0] + bf2f((unsigned short)qf[s][5]) * k1[1] + bf2f((unsigned short)qf[s][6]) * k1[2] + bf2f((unsigned short)qf[s][7]) * k1[3];
;                     }
;                 }
;                 a += __shfl_xor(a, 32);
;                 g[j] = a;
;             }
	v_lshlrev_b32_e32 v66, 3, v82
	v_lshl_add_u32 v66, v66, 2, 0
	v_add_u32_e32 v66, 0x13a00, v66
	ds_read_b128 v[68:71], v66
	ds_read_b128 v[72:75], v66 offset:16
	s_cmp_lg_u32 s18, 4
	v_mov_b32_e32 v67, 0
	s_cselect_b64 s[4:5], -1, 0
	s_waitcnt lgkmcnt(1)
	v_mul_f32_e32 v69, v69, v23
	v_fmac_f32_e32 v69, v68, v22
	v_fmac_f32_e32 v69, v70, v16
	v_fmac_f32_e32 v69, v71, v17
	v_add_f32_e32 v68, 0, v69
	s_waitcnt lgkmcnt(0)
	v_mul_f32_e32 v69, v73, v21
	v_fmac_f32_e32 v69, v72, v20
	v_fmac_f32_e32 v69, v74, v15
	v_fmac_f32_e32 v69, v75, v14
	v_add_f32_e32 v72, v68, v69
	ds_read_b128 v[68:71], v66 offset:64
	s_cmp_eq_u32 s18, 4
	s_waitcnt lgkmcnt(0)
	v_mul_f32_e32 v69, v69, v29
	v_fmac_f32_e32 v69, v68, v28
	v_fmac_f32_e32 v69, v70, v18
	v_fmac_f32_e32 v69, v71, v19
	v_add_f32_e32 v72, v72, v69
	ds_read_b128 v[68:71], v66 offset:80
	s_waitcnt lgkmcnt(0)
	v_mul_f32_e32 v69, v69, v27
	v_fmac_f32_e32 v69, v68, v26
	v_fmac_f32_e32 v69, v70, v13
	v_fmac_f32_e32 v69, v71, v12
	v_add_f32_e32 v72, v72, v69
	ds_read_b128 v[68:71], v66 offset:128
	s_waitcnt lgkmcnt(0)
	v_mul_f32_e32 v69, v69, v35
	v_fmac_f32_e32 v69, v68, v34
	v_fmac_f32_e32 v69, v70, v24
	v_fmac_f32_e32 v69, v71, v25
	v_add_f32_e32 v72, v72, v69
	ds_read_b128 v[68:71], v66 offset:144
	s_waitcnt lgkmcnt(0)
	v_mul_f32_e32 v69, v69, v33
	v_fmac_f32_e32 v69, v68, v32
	v_fmac_f32_e32 v69, v70, v11
	v_fmac_f32_e32 v69, v71, v10
	v_add_f32_e32 v72, v72, v69
	ds_read_b128 v[68:71], v66 offset:192
	s_waitcnt lgkmcnt(0)
	v_mul_f32_e32 v69, v69, v43
	v_fmac_f32_e32 v69, v68, v42
	v_fmac_f32_e32 v69, v70, v30
	v_fmac_f32_e32 v69, v71, v31
	v_add_f32_e32 v72, v72, v69
	ds_read_b128 v[68:71], v66 offset:208
	s_waitcnt lgkmcnt(0)
	v_mul_f32_e32 v69, v69, v41
	v_fmac_f32_e32 v69, v68, v40
	v_fmac_f32_e32 v69, v70, v9
	v_fmac_f32_e32 v69, v71, v8
	v_add_f32_e32 v72, v72, v69
	ds_read_b128 v[68:71], v66 offset:256
	s_waitcnt lgkmcnt(0)
	v_mul_f32_e32 v69, v69, v49
	v_fmac_f32_e32 v69, v68, v48
	v_fmac_f32_e32 v69, v70, v38
	v_fmac_f32_e32 v69, v71, v39
	v_add_f32_e32 v72, v72, v69
	ds_read_b128 v[68:71], v66 offset:272
	s_waitcnt lgkmcnt(0)
	v_mul_f32_e32 v69, v69, v47
	v_fmac_f32_e32 v69, v68, v46
	v_fmac_f32_e32 v69, v70, v7
	v_fmac_f32_e32 v69, v71, v6
	v_add_f32_e32 v72, v72, v69
	ds_read_b128 v[68:71], v66 offset:320
	s_waitcnt lgkmcnt(0)
	v_mul_f32_e32 v69, v69, v55
	v_fmac_f32_e32 v69, v68, v54
	v_fmac_f32_e32 v69, v70, v44
	v_fmac_f32_e32 v69, v71, v45
	v_add_f32_e32 v72, v72, v69
	ds_read_b128 v[68:71], v66 offset:336
	s_waitcnt lgkmcnt(0)
	v_mul_f32_e32 v69, v69, v53
	v_fmac_f32_e32 v69, v68, v52
	v_fmac_f32_e32 v69, v70, v5
	v_fmac_f32_e32 v69, v71, v4
	v_add_f32_e32 v72, v72, v69
	ds_read_b128 v[68:71], v66 offset:384
	s_waitcnt lgkmcnt(0)
	v_mul_f32_e32 v69, v69, v61
	v_fmac_f32_e32 v69, v68, v60
	v_fmac_f32_e32 v69, v70, v50
	v_fmac_f32_e32 v69, v71, v51
	v_add_f32_e32 v72, v72, v69
	ds_read_b128 v[68:71], v66 offset:400
	s_waitcnt lgkmcnt(0)
	v_mul_f32_e32 v69, v69, v59
	v_fmac_f32_e32 v69, v68, v58
	v_fmac_f32_e32 v69, v70, v3
	v_fmac_f32_e32 v69, v71, v2
	v_add_f32_e32 v72, v72, v69
	ds_read_b128 v[68:71], v66 offset:448
	s_waitcnt lgkmcnt(0)
	v_mul_f32_e32 v69, v69, v65
	v_fmac_f32_e32 v69, v68, v64
	v_fmac_f32_e32 v69, v70, v56
	v_fmac_f32_e32 v69, v71, v57
	v_add_f32_e32 v72, v72, v69
	ds_read_b128 v[68:71], v66 offset:464
	s_waitcnt lgkmcnt(0)
	v_mul_f32_e32 v69, v69, v63
	v_fmac_f32_e32 v69, v68, v62
	v_fmac_f32_e32 v69, v70, v1
	v_fmac_f32_e32 v69, v71, v0
	v_add_f32_e32 v68, v72, v69
	ds_read_b128 v[70:73], v66 offset:512
	ds_bpermute_b32 v69, v170, v68
	s_waitcnt lgkmcnt(1)
	v_mul_f32_e32 v71, v71, v23
	v_fmac_f32_e32 v71, v70, v22
	v_fmac_f32_e32 v71, v72, v16
	v_fmac_f32_e32 v71, v73, v17
	v_add_f32_e32 v74, 0, v71
	ds_read_b128 v[70:73], v66 offset:528
	s_waitcnt lgkmcnt(0)
	v_mul_f32_e32 v71, v71, v21
	v_fmac_f32_e32 v71, v70, v20
	v_fmac_f32_e32 v71, v72, v15
	v_fmac_f32_e32 v71, v73, v14
	v_add_f32_e32 v74, v74, v71
	ds_read_b128 v[70:73], v66 offset:576
	s_waitcnt lgkmcnt(0)
	v_mul_f32_e32 v71, v71, v29
	v_fmac_f32_e32 v71, v70, v28
	v_fmac_f32_e32 v71, v72, v18
	v_fmac_f32_e32 v71, v73, v19
	v_add_f32_e32 v74, v74, v71
	ds_read_b128 v[70:73], v66 offset:592
	s_waitcnt lgkmcnt(0)
	v_mul_f32_e32 v71, v71, v27
	v_fmac_f32_e32 v71, v70, v26
	v_fmac_f32_e32 v71, v72, v13
	v_fmac_f32_e32 v71, v73, v12
	v_add_f32_e32 v74, v74, v71
	ds_read_b128 v[70:73], v66 offset:640
	s_waitcnt lgkmcnt(0)
	v_mul_f32_e32 v71, v71, v35
	v_fmac_f32_e32 v71, v70, v34
	v_fmac_f32_e32 v71, v72, v24
	v_fmac_f32_e32 v71, v73, v25
	v_add_f32_e32 v74, v74, v71
	ds_read_b128 v[70:73], v66 offset:656
	s_waitcnt lgkmcnt(0)
	v_mul_f32_e32 v71, v71, v33
	v_fmac_f32_e32 v71, v70, v32
	v_fmac_f32_e32 v71, v72, v11
	v_fmac_f32_e32 v71, v73, v10
	v_add_f32_e32 v74, v74, v71
	ds_read_b128 v[70:73], v66 offset:704
	s_waitcnt lgkmcnt(0)
	v_mul_f32_e32 v71, v71, v43
	v_fmac_f32_e32 v71, v70, v42
	v_fmac_f32_e32 v71, v72, v30
	v_fmac_f32_e32 v71, v73, v31
	v_add_f32_e32 v74, v74, v71
	ds_read_b128 v[70:73], v66 offset:720
	s_waitcnt lgkmcnt(0)
	v_mul_f32_e32 v71, v71, v41
	v_fmac_f32_e32 v71, v70, v40
	v_fmac_f32_e32 v71, v72, v9
	v_fmac_f32_e32 v71, v73, v8
	v_add_f32_e32 v74, v74, v71
	ds_read_b128 v[70:73], v66 offset:768
	s_waitcnt lgkmcnt(0)
	v_mul_f32_e32 v71, v71, v49
	v_fmac_f32_e32 v71, v70, v48
	v_fmac_f32_e32 v71, v72, v38
	v_fmac_f32_e32 v71, v73, v39
	v_add_f32_e32 v74, v74, v71
	ds_read_b128 v[70:73], v66 offset:784
	s_waitcnt lgkmcnt(0)
	v_mul_f32_e32 v71, v71, v47
	v_fmac_f32_e32 v71, v70, v46
	v_fmac_f32_e32 v71, v72, v7
	v_fmac_f32_e32 v71, v73, v6
	v_add_f32_e32 v74, v74, v71
	ds_read_b128 v[70:73], v66 offset:832
	s_waitcnt lgkmcnt(0)
; #define LAS __attribute__((address_space(3)))
; __device__ __forceinline__ float bf2f(unsigned short v) { return __uint_as_float(((unsigned)v) << 16); }
; template <int DQK, bool MOBA>
; __device__ __forceinline__ void attn_unit(const Args& A, int b, int h, int qb, lptr lds) {
;     ...
;             for (int j = 0; j < 7; ++j) {
;                 float a = 0.f;
;                 if (j < own) {
; #pragma unroll
;                     for (int s = 0; s < NS; ++s) {
;                         const f32x4 k0 = *(const LAS f32x4*)(km + j * 128 + 16 * s + 8 * hi), k1 = *(const LAS f32x4*)(km + j * 128 + 16 * s + 8 * hi + 4);
;                         a += bf2f((unsigned short)qf[s][0]) * k0[0] + bf2f((unsigned short)qf[s][1]) * k0[1] + bf2f((unsigned short)qf[s][2]) * k0[2] + bf2f((unsigned short)qf[s][3]) * k0[3];
;                         a += bf2f((unsigned short)qf[s][4]) * k1[0] + bf2f((unsigned short)qf[s][5]) * k1[1] + bf2f((unsigned short)qf[s][6]) * k1[2] + bf2f((unsigned short)qf[s][7]) * k1[3];
;                     }
;                 }
;                 a += __shfl_xor(a, 32);
;                 g[j] = a;
	v_mul_f32_e32 v71, v71, v55
	v_fmac_f32_e32 v71, v70, v54
	v_fmac_f32_e32 v71, v72, v44
	v_fmac_f32_e32 v71, v73, v45
	v_add_f32_e32 v74, v74, v71
	ds_read_b128 v[70:73], v66 offset:848
	s_waitcnt lgkmcnt(0)
	v_mul_f32_e32 v71, v71, v53
	v_fmac_f32_e32 v71, v70, v52
	v_fmac_f32_e32 v71, v72, v5
	v_fmac_f32_e32 v71, v73, v4
	v_add_f32_e32 v74, v74, v71
	ds_read_b128 v[70:73], v66 offset:896
	s_waitcnt lgkmcnt(0)
	v_mul_f32_e32 v71, v71, v61
	v_fmac_f32_e32 v71, v70, v60
	v_fmac_f32_e32 v71, v72, v50
	v_fmac_f32_e32 v71, v73, v51
	v_add_f32_e32 v74, v74, v71
	ds_read_b128 v[70:73], v66 offset:912
	s_waitcnt lgkmcnt(0)
	v_mul_f32_e32 v71, v71, v59
	v_fmac_f32_e32 v71, v70, v58
	v_fmac_f32_e32 v71, v72, v3
	v_fmac_f32_e32 v71, v73, v2
	v_add_f32_e32 v74, v74, v71
	ds_read_b128 v[70:73], v66 offset:960
	s_waitcnt lgkmcnt(0)
	v_mul_f32_e32 v71, v71, v65
	v_fmac_f32_e32 v71, v70, v64
	v_fmac_f32_e32 v71, v72, v56
	v_fmac_f32_e32 v71, v73, v57
	v_add_f32_e32 v74, v74, v71
	ds_read_b128 v[70:73], v66 offset:976
	s_waitcnt lgkmcnt(0)
	v_mul_f32_e32 v71, v71, v63
	v_fmac_f32_e32 v71, v70, v62
	v_fmac_f32_e32 v71, v72, v1
	v_fmac_f32_e32 v71, v73, v0
	v_add_f32_e32 v70, v74, v71
	ds_read_b128 v[72:75], v66 offset:1024
	ds_bpermute_b32 v71, v170, v70
	s_waitcnt lgkmcnt(1)
	v_mul_f32_e32 v73, v73, v23
	v_fmac_f32_e32 v73, v72, v22
	v_fmac_f32_e32 v73, v74, v16
	v_fmac_f32_e32 v73, v75, v17
	v_add_f32_e32 v76, 0, v73
	ds_read_b128 v[72:75], v66 offset:1040
	s_waitcnt lgkmcnt(0)
	v_mul_f32_e32 v73, v73, v21
	v_fmac_f32_e32 v73, v72, v20
	v_fmac_f32_e32 v73, v74, v15
	v_fmac_f32_e32 v73, v75, v14
	v_add_f32_e32 v76, v76, v73
	ds_read_b128 v[72:75], v66 offset:1088
	s_waitcnt lgkmcnt(0)
	v_mul_f32_e32 v73, v73, v29
	v_fmac_f32_e32 v73, v72, v28
	v_fmac_f32_e32 v73, v74, v18
	v_fmac_f32_e32 v73, v75, v19
	v_add_f32_e32 v76, v76, v73
	ds_read_b128 v[72:75], v66 offset:1104
	s_waitcnt lgkmcnt(0)
	v_mul_f32_e32 v73, v73, v27
	v_fmac_f32_e32 v73, v72, v26
	v_fmac_f32_e32 v73, v74, v13
	v_fmac_f32_e32 v73, v75, v12
	v_add_f32_e32 v76, v76, v73
	ds_read_b128 v[72:75], v66 offset:1152
	s_waitcnt lgkmcnt(0)
	v_mul_f32_e32 v73, v73, v35
	v_fmac_f32_e32 v73, v72, v34
	v_fmac_f32_e32 v73, v74, v24
	v_fmac_f32_e32 v73, v75, v25
	v_add_f32_e32 v76, v76, v73
	ds_read_b128 v[72:75], v66 offset:1168
	s_waitcnt lgkmcnt(0)
	v_mul_f32_e32 v73, v73, v33
	v_fmac_f32_e32 v73, v72, v32
	v_fmac_f32_e32 v73, v74, v11
	v_fmac_f32_e32 v73, v75, v10
	v_add_f32_e32 v76, v76, v73
	ds_read_b128 v[72:75], v66 offset:1216
	s_waitcnt lgkmcnt(0)
	v_mul_f32_e32 v73, v73, v43
	v_fmac_f32_e32 v73, v72, v42
	v_fmac_f32_e32 v73, v74, v30
	v_fmac_f32_e32 v73, v75, v31
	v_add_f32_e32 v76, v76, v73
	ds_read_b128 v[72:75], v66 offset:1232
	s_waitcnt lgkmcnt(0)
	v_mul_f32_e32 v73, v73, v41
	v_fmac_f32_e32 v73, v72, v40
	v_fmac_f32_e32 v73, v74, v9
	v_fmac_f32_e32 v73, v75, v8
	v_add_f32_e32 v76, v76, v73
	ds_read_b128 v[72:75], v66 offset:1280
	s_waitcnt lgkmcnt(0)
	v_mul_f32_e32 v73, v73, v49
	v_fmac_f32_e32 v73, v72, v48
	v_fmac_f32_e32 v73, v74, v38
	v_fmac_f32_e32 v73, v75, v39
	v_add_f32_e32 v76, v76, v73
	ds_read_b128 v[72:75], v66 offset:1296
	s_waitcnt lgkmcnt(0)
	v_mul_f32_e32 v73, v73, v47
	v_fmac_f32_e32 v73, v72, v46
	v_fmac_f32_e32 v73, v74, v7
	v_fmac_f32_e32 v73, v75, v6
	v_add_f32_e32 v76, v76, v73
	ds_read_b128 v[72:75], v66 offset:1344
	s_waitcnt lgkmcnt(0)
	v_mul_f32_e32 v73, v73, v55
	v_fmac_f32_e32 v73, v72, v54
	v_fmac_f32_e32 v73, v74, v44
	v_fmac_f32_e32 v73, v75, v45
	v_add_f32_e32 v76, v76, v73
	ds_read_b128 v[72:75], v66 offset:1360
	s_waitcnt lgkmcnt(0)
	v_mul_f32_e32 v73, v73, v53
	v_fmac_f32_e32 v73, v72, v52
	v_fmac_f32_e32 v73, v74, v5
	v_fmac_f32_e32 v73, v75, v4
	v_add_f32_e32 v76, v76, v73
	ds_read_b128 v[72:75], v66 offset:1408
	s_waitcnt lgkmcnt(0)
	v_mul_f32_e32 v73, v73, v61
	v_fmac_f32_e32 v73, v72, v60
	v_fmac_f32_e32 v73, v74, v50
	v_fmac_f32_e32 v73, v75, v51
	v_add_f32_e32 v76, v76, v73
	ds_read_b128 v[72:75], v66 offset:1424
	s_waitcnt lgkmcnt(0)
	v_mul_f32_e32 v73, v73, v59
	v_fmac_f32_e32 v73, v72, v58
	v_fmac_f32_e32 v73, v74, v3
	v_fmac_f32_e32 v73, v75, v2
	v_add_f32_e32 v76, v76, v73
	ds_read_b128 v[72:75], v66 offset:1472
	s_waitcnt lgkmcnt(0)
	v_mul_f32_e32 v73, v73, v65
	v_fmac_f32_e32 v73, v72, v64
	v_fmac_f32_e32 v73, v74, v56
	v_fmac_f32_e32 v73, v75, v57
	v_add_f32_e32 v76, v76, v73
	ds_read_b128 v[72:75], v66 offset:1488
	s_waitcnt lgkmcnt(0)
	v_mul_f32_e32 v73, v73, v63
	v_fmac_f32_e32 v73, v72, v62
	v_fmac_f32_e32 v73, v74, v1
	v_fmac_f32_e32 v73, v75, v0
	v_add_f32_e32 v72, v76, v73
	ds_read_b128 v[74:77], v66 offset:1536
	ds_bpermute_b32 v73, v170, v72
	s_waitcnt lgkmcnt(1)
	v_mul_f32_e32 v75, v75, v23
	v_fmac_f32_e32 v75, v74, v22
	v_fmac_f32_e32 v75, v76, v16
	v_fmac_f32_e32 v75, v77, v17
	v_add_f32_e32 v78, 0, v75
	ds_read_b128 v[74:77], v66 offset:1552
	s_waitcnt lgkmcnt(0)
	v_mul_f32_e32 v75, v75, v21
	v_fmac_f32_e32 v75, v74, v20
	v_fmac_f32_e32 v75, v76, v15
	v_fmac_f32_e32 v75, v77, v14
	v_add_f32_e32 v78, v78, v75
	ds_read_b128 v[74:77], v66 offset:1600
	s_waitcnt lgkmcnt(0)
	v_mul_f32_e32 v75, v75, v29
	v_fmac_f32_e32 v75, v74, v28
	v_fmac_f32_e32 v75, v76, v18
	v_fmac_f32_e32 v75, v77, v19
	v_add_f32_e32 v78, v78, v75
	ds_read_b128 v[74:77], v66 offset:1616
	s_waitcnt lgkmcnt(0)
	v_mul_f32_e32 v75, v75, v27
	v_fmac_f32_e32 v75, v74, v26
	v_fmac_f32_e32 v75, v76, v13
	v_fmac_f32_e32 v75, v77, v12
	v_add_f32_e32 v78, v78, v75
	ds_read_b128 v[74:77], v66 offset:1664
	s_waitcnt lgkmcnt(0)
	v_mul_f32_e32 v75, v75, v35
	v_fmac_f32_e32 v75, v74, v34
	v_fmac_f32_e32 v75, v76, v24
	v_fmac_f32_e32 v75, v77, v25
	v_add_f32_e32 v78, v78, v75
	ds_read_b128 v[74:77], v66 offset:1680
	s_waitcnt lgkmcnt(0)
; #define LAS __attribute__((address_space(3)))
; __device__ __forceinline__ float bf2f(unsigned short v) { return __uint_as_float(((unsigned)v) << 16); }
; template <int DQK, bool MOBA>
; __device__ __forceinline__ void attn_unit(const Args& A, int b, int h, int qb, lptr lds) {
;     ...
;             for (int j = 0; j < 7; ++j) {
;                 float a = 0.f;
;                 if (j < own) {
; #pragma unroll
;                     for (int s = 0; s < NS; ++s) {
;                         const f32x4 k0 = *(const LAS f32x4*)(km + j * 128 + 16 * s + 8 * hi), k1 = *(const LAS f32x4*)(km + j * 128 + 16 * s + 8 * hi + 4);
;                         a += bf2f((unsigned short)qf[s][0]) * k0[0] + bf2f((unsigned short)qf[s][1]) * k0[1] + bf2f((unsigned short)qf[s][2]) * k0[2] + bf2f((unsigned short)qf[s][3]) * k0[3];
;                         a += bf2f((unsigned short)qf[s][4]) * k1[0] + bf2f((unsigned short)qf[s][5]) * k1[1] + bf2f((unsigned short)qf[s][6]) * k1[2] + bf2f((unsigned short)qf[s][7]) * k1[3];
;                     }
;                 }
;                 a += __shfl_xor(a, 32);
;                 g[j] = a;
	v_mul_f32_e32 v75, v75, v33
	v_fmac_f32_e32 v75, v74, v32
	v_fmac_f32_e32 v75, v76, v11
	v_fmac_f32_e32 v75, v77, v10
	v_add_f32_e32 v78, v78, v75
	ds_read_b128 v[74:77], v66 offset:1728
	s_waitcnt lgkmcnt(0)
	v_mul_f32_e32 v75, v75, v43
	v_fmac_f32_e32 v75, v74, v42
	v_fmac_f32_e32 v75, v76, v30
	v_fmac_f32_e32 v75, v77, v31
	v_add_f32_e32 v78, v78, v75
	ds_read_b128 v[74:77], v66 offset:1744
	s_waitcnt lgkmcnt(0)
	v_mul_f32_e32 v75, v75, v41
	v_fmac_f32_e32 v75, v74, v40
	v_fmac_f32_e32 v75, v76, v9
	v_fmac_f32_e32 v75, v77, v8
	v_add_f32_e32 v78, v78, v75
	ds_read_b128 v[74:77], v66 offset:1792
	s_waitcnt lgkmcnt(0)
	v_mul_f32_e32 v75, v75, v49
	v_fmac_f32_e32 v75, v74, v48
	v_fmac_f32_e32 v75, v76, v38
	v_fmac_f32_e32 v75, v77, v39
	v_add_f32_e32 v78, v78, v75
	ds_read_b128 v[74:77], v66 offset:1808
	s_waitcnt lgkmcnt(0)
	v_mul_f32_e32 v75, v75, v47
	v_fmac_f32_e32 v75, v74, v46
	v_fmac_f32_e32 v75, v76, v7
	v_fmac_f32_e32 v75, v77, v6
	v_add_f32_e32 v78, v78, v75
	ds_read_b128 v[74:77], v66 offset:1856
	s_waitcnt lgkmcnt(0)
	v_mul_f32_e32 v75, v75, v55
	v_fmac_f32_e32 v75, v74, v54
	v_fmac_f32_e32 v75, v76, v44
	v_fmac_f32_e32 v75, v77, v45
	v_add_f32_e32 v78, v78, v75
	ds_read_b128 v[74:77], v66 offset:1872
	s_waitcnt lgkmcnt(0)
	v_mul_f32_e32 v75, v75, v53
	v_fmac_f32_e32 v75, v74, v52
	v_fmac_f32_e32 v75, v76, v5
	v_fmac_f32_e32 v75, v77, v4
	v_add_f32_e32 v78, v78, v75
	ds_read_b128 v[74:77], v66 offset:1920
	s_waitcnt lgkmcnt(0)
	v_mul_f32_e32 v75, v75, v61
	v_fmac_f32_e32 v75, v74, v60
	v_fmac_f32_e32 v75, v76, v50
	v_fmac_f32_e32 v75, v77, v51
	v_add_f32_e32 v78, v78, v75
	ds_read_b128 v[74:77], v66 offset:1936
	s_waitcnt lgkmcnt(0)
	v_mul_f32_e32 v75, v75, v59
	v_fmac_f32_e32 v75, v74, v58
	v_fmac_f32_e32 v75, v76, v3
	v_fmac_f32_e32 v75, v77, v2
	v_add_f32_e32 v78, v78, v75
	ds_read_b128 v[74:77], v66 offset:1984
	s_waitcnt lgkmcnt(0)
	v_mul_f32_e32 v75, v75, v65
	v_fmac_f32_e32 v75, v74, v64
	v_fmac_f32_e32 v75, v76, v56
	v_fmac_f32_e32 v75, v77, v57
	v_add_f32_e32 v78, v78, v75
	ds_read_b128 v[74:77], v66 offset:2000
	s_waitcnt lgkmcnt(0)
	v_mul_f32_e32 v75, v75, v63
	v_fmac_f32_e32 v75, v74, v62
	v_fmac_f32_e32 v75, v76, v1
	v_fmac_f32_e32 v75, v77, v0
	v_add_f32_e32 v74, v78, v75
	ds_bpermute_b32 v75, v170, v74
	v_mov_b32_e32 v76, 0
	s_cbranch_scc1 .LBB0_764
; #define LAS __attribute__((address_space(3)))
; __device__ __forceinline__ float bf2f(unsigned short v) { return __uint_as_float(((unsigned)v) << 16); }
; template <int DQK, bool MOBA>
; __device__ __forceinline__ void attn_unit(const Args& A, int b, int h, int qb, lptr lds) {
;     ...
;             for (int j = 0; j < 7; ++j) {
;                 float a = 0.f;
;                 if (j < own) {
; #pragma unroll
;                     for (int s = 0; s < NS; ++s) {
;                         const f32x4 k0 = *(const LAS f32x4*)(km + j * 128 + 16 * s + 8 * hi), k1 = *(const LAS f32x4*)(km + j * 128 + 16 * s + 8 * hi + 4);
;                         a += bf2f((unsigned short)qf[s][0]) * k0[0] + bf2f((unsigned short)qf[s][1]) * k0[1] + bf2f((unsigned short)qf[s][2]) * k0[2] + bf2f((unsigned short)qf[s][3]) * k0[3];
;                         a += bf2f((unsigned short)qf[s][4]) * k1[0] + bf2f((unsigned short)qf[s][5]) * k1[1] + bf2f((unsigned short)qf[s][6]) * k1[2] + bf2f((unsigned short)qf[s][7]) * k1[3];
;                     }
;                 }
;                 a += __shfl_xor(a, 32);
;                 g[j] = a;
	ds_read_b128 v[76:79], v66 offset:2048
	ds_read_b128 v[90:93], v66 offset:2064
	v_mov_b32_e32 v96, v34
	v_mov_b32_e32 v97, v32
	s_waitcnt lgkmcnt(1)
	v_mul_f32_e32 v77, v77, v23
	v_fmac_f32_e32 v77, v76, v22
	v_fmac_f32_e32 v77, v78, v16
	v_fmac_f32_e32 v77, v79, v17
	v_add_f32_e32 v76, 0, v77
	s_waitcnt lgkmcnt(0)
	v_mul_f32_e32 v77, v91, v21
	v_fmac_f32_e32 v77, v90, v20
	v_fmac_f32_e32 v77, v92, v15
	v_fmac_f32_e32 v77, v93, v14
	v_add_f32_e32 v94, v76, v77
	ds_read_b128 v[76:79], v66 offset:2112
	ds_read_b128 v[90:93], v66 offset:2128
	s_waitcnt lgkmcnt(1)
	v_mul_f32_e32 v77, v77, v29
	v_fmac_f32_e32 v77, v76, v28
	v_fmac_f32_e32 v77, v78, v18
	v_fmac_f32_e32 v77, v79, v19
	v_add_f32_e32 v76, v94, v77
	s_waitcnt lgkmcnt(0)
	v_mul_f32_e32 v77, v91, v27
	v_fmac_f32_e32 v77, v90, v26
	v_fmac_f32_e32 v77, v92, v13
	v_fmac_f32_e32 v77, v93, v12
	v_add_f32_e32 v98, v76, v77
	ds_read_b128 v[76:79], v66 offset:2176
	ds_read_b128 v[90:93], v66 offset:2192
	s_waitcnt lgkmcnt(1)
	v_mov_b32_e32 v94, v76
	s_waitcnt lgkmcnt(0)
	v_mov_b32_e32 v95, v90
	v_mov_b32_e32 v90, v77
	v_mov_b32_e32 v76, v35
	v_mov_b32_e32 v77, v33
	v_pk_mul_f32 v[76:77], v[90:91], v[76:77]
	v_mov_b32_e32 v90, v78
	v_pk_fma_f32 v[76:77], v[94:95], v[96:97], v[76:77]
	v_mov_b32_e32 v91, v92
	v_mov_b32_e32 v94, v24
	v_mov_b32_e32 v95, v11
	v_pk_fma_f32 v[76:77], v[90:91], v[94:95], v[76:77]
	v_mov_b32_e32 v92, v79
	v_pk_mov_b32 v[78:79], v[24:25], v[10:11] op_sel:[1,0]
	v_mov_b32_e32 v96, v42
	v_pk_fma_f32 v[76:77], v[92:93], v[78:79], v[76:77]
	v_mov_b32_e32 v97, v40
	v_add_f32_e32 v76, v98, v76
	v_add_f32_e32 v98, v76, v77
	ds_read_b128 v[76:79], v66 offset:2240
	ds_read_b128 v[90:93], v66 offset:2256
	s_waitcnt lgkmcnt(1)
	v_mov_b32_e32 v94, v76
	s_waitcnt lgkmcnt(0)
	v_mov_b32_e32 v95, v90
	v_mov_b32_e32 v90, v77
	v_mov_b32_e32 v76, v43
	v_mov_b32_e32 v77, v41
	v_pk_mul_f32 v[76:77], v[90:91], v[76:77]
	v_mov_b32_e32 v90, v78
	v_pk_fma_f32 v[76:77], v[94:95], v[96:97], v[76:77]
	v_mov_b32_e32 v91, v92
	v_mov_b32_e32 v94, v30
	v_mov_b32_e32 v95, v9
	v_pk_fma_f32 v[76:77], v[90:91], v[94:95], v[76:77]
	v_mov_b32_e32 v92, v79
	v_pk_mov_b32 v[78:79], v[30:31], v[8:9] op_sel:[1,0]
	v_mov_b32_e32 v96, v48
	v_pk_fma_f32 v[76:77], v[92:93], v[78:79], v[76:77]
	v_mov_b32_e32 v97, v46
	v_add_f32_e32 v76, v98, v76
	v_add_f32_e32 v98, v76, v77
	ds_read_b128 v[76:79], v66 offset:2304
	ds_read_b128 v[90:93], v66 offset:2320
	s_waitcnt lgkmcnt(1)
	v_mov_b32_e32 v94, v76
	s_waitcnt lgkmcnt(0)
	v_mov_b32_e32 v95, v90
	v_mov_b32_e32 v90, v77
	v_mov_b32_e32 v76, v49
	v_mov_b32_e32 v77, v47
	v_pk_mul_f32 v[76:77], v[90:91], v[76:77]
	v_mov_b32_e32 v90, v78
	v_pk_fma_f32 v[76:77], v[94:95], v[96:97], v[76:77]
	v_mov_b32_e32 v91, v92
	v_mov_b32_e32 v94, v38
	v_mov_b32_e32 v95, v7
	v_pk_fma_f32 v[76:77], v[90:91], v[94:95], v[76:77]
	v_mov_b32_e32 v92, v79
	v_pk_mov_b32 v[78:79], v[38:39], v[6:7] op_sel:[1,0]
	v_mov_b32_e32 v96, v54
	v_pk_fma_f32 v[76:77], v[92:93], v[78:79], v[76:77]
	v_mov_b32_e32 v97, v52
	v_add_f32_e32 v76, v98, v76
	v_add_f32_e32 v98, v76, v77
	ds_read_b128 v[76:79], v66 offset:2368
	ds_read_b128 v[90:93], v66 offset:2384
	s_waitcnt lgkmcnt(1)
	v_mov_b32_e32 v94, v76
	s_waitcnt lgkmcnt(0)
	v_mov_b32_e32 v95, v90
	v_mov_b32_e32 v90, v77
	v_mov_b32_e32 v76, v55
	v_mov_b32_e32 v77, v53
	v_pk_mul_f32 v[76:77], v[90:91], v[76:77]
	v_mov_b32_e32 v90, v78
	v_pk_fma_f32 v[76:77], v[94:95], v[96:97], v[76:77]
	v_mov_b32_e32 v91, v92
	v_mov_b32_e32 v94, v44
	v_mov_b32_e32 v95, v5
	v_pk_fma_f32 v[76:77], v[90:91], v[94:95], v[76:77]
	v_mov_b32_e32 v92, v79
	v_pk_mov_b32 v[78:79], v[44:45], v[4:5] op_sel:[1,0]
	v_mov_b32_e32 v96, v60
	v_pk_fma_f32 v[76:77], v[92:93], v[78:79], v[76:77]
	v_mov_b32_e32 v97, v58
	v_add_f32_e32 v76, v98, v76
	v_add_f32_e32 v98, v76, v77
	ds_read_b128 v[76:79], v66 offset:2432
	ds_read_b128 v[90:93], v66 offset:2448
	s_waitcnt lgkmcnt(1)
	v_mov_b32_e32 v94, v76
	s_waitcnt lgkmcnt(0)
	v_mov_b32_e32 v95, v90
	v_mov_b32_e32 v90, v77
	v_mov_b32_e32 v76, v61
	v_mov_b32_e32 v77, v59
	v_pk_mul_f32 v[76:77], v[90:91], v[76:77]
	v_mov_b32_e32 v90, v78
	v_pk_fma_f32 v[76:77], v[94:95], v[96:97], v[76:77]
	v_mov_b32_e32 v91, v92
	v_mov_b32_e32 v94, v50
	v_mov_b32_e32 v95, v3
	v_pk_fma_f32 v[76:77], v[90:91], v[94:95], v[76:77]
	v_mov_b32_e32 v92, v79
	v_pk_mov_b32 v[78:79], v[50:51], v[2:3] op_sel:[1,0]
	v_mov_b32_e32 v96, v64
	v_pk_fma_f32 v[76:77], v[92:93], v[78:79], v[76:77]
	v_mov_b32_e32 v97, v62
	v_add_f32_e32 v76, v98, v76
	v_add_f32_e32 v98, v76, v77
	ds_read_b128 v[76:79], v66 offset:2496
	ds_read_b128 v[90:93], v66 offset:2512
	s_waitcnt lgkmcnt(1)
	v_mov_b32_e32 v94, v76
	s_waitcnt lgkmcnt(0)
	v_mov_b32_e32 v95, v90
	v_mov_b32_e32 v90, v77
	v_mov_b32_e32 v76, v65
	v_mov_b32_e32 v77, v63
	v_pk_mul_f32 v[76:77], v[90:91], v[76:77]
	v_mov_b32_e32 v90, v78
	v_pk_fma_f32 v[76:77], v[94:95], v[96:97], v[76:77]
	v_mov_b32_e32 v91, v92
	v_mov_b32_e32 v94, v56
	v_mov_b32_e32 v95, v1
	v_pk_fma_f32 v[76:77], v[90:91], v[94:95], v[76:77]
	v_mov_b32_e32 v92, v79
	v_pk_mov_b32 v[78:79], v[56:57], v[0:1] op_sel:[1,0]
	s_nop 0
	v_pk_fma_f32 v[76:77], v[92:93], v[78:79], v[76:77]
	s_nop 0
	v_add_f32_e32 v76, v98, v76
	v_add_f32_e32 v76, v76, v77

; template <int DQK, bool MOBA>
; __device__ __forceinline__ void attn_unit(const Args& A, int b, int h, int qb, lptr lds) {
;     ...
;         qss += __shfl_xor(qss, 32);
;         float gmx = fmaxf(fabsf(A.gk_n[lane]), fabsf(A.gk_n[lane + 64]));
;         float grx = (DQK == 192) ? fabsf(A.gk_r[lane]) : 0.f;
;         float bmx = (MOBA && lane < 32) ? fabsf(A.relb[lane * 8 + h]) * 1.4426950408889634f : 0.f;
; #pragma unroll
;         for (int o_ = 1; o_ < 64; o_ <<= 1) { gmx = fmaxf(gmx, __shfl_xor(gmx, o_)); grx = fmaxf(grx, __shfl_xor(grx, o_)); bmx = fmaxf(bmx, __shfl_xor(bmx, o_)); }
;         negm = -(sqrtf(qss * (128.0f * gmx * gmx + 64.0f * grx * grx)) * 1.01f + bmx + 0.01f);
;     ...
;     f32x16 o[4];
; #pragma unroll
;     for (int d = 0; d < 4; ++d)
; #pragma unroll
;         for (int r = 0; r < 16; ++r) o[d][r] = 0.f;
;     float lrow = 0.f;
;     ATT_LOAD(0); ATT_WRITE(0);
;     if (NT > 1) ATT_LOAD(1);
.LBB0_773:
	s_or_b64 exec, exec, s[0:1]
	s_waitcnt vmcnt(0)
	v_max_f32_e64 v1, |v1|, |v1|
	v_max_f32_e64 v0, |v0|, |v0|
	v_max_f32_e32 v0, v0, v1
	v_xor_b32_e32 v1, 1, v206
	v_cmp_lt_i32_e32 vcc, v1, v89
	s_mul_i32 s15, s42, 0x1800
	s_mul_hi_i32 s13, s42, 0x1800
	v_cndmask_b32_e32 v1, v206, v1, vcc
	v_lshlrev_b32_e32 v1, 2, v1
	ds_bpermute_b32 v3, v1, v0
	ds_bpermute_b32 v1, v1, v2
	v_max_f32_e32 v2, v2, v2
	s_add_u32 s0, s95, s15
	v_ashrrev_i32_e32 v22, 4, v162
	s_waitcnt lgkmcnt(1)
	v_max_f32_e32 v3, v3, v3
	s_waitcnt lgkmcnt(0)
	v_max_f32_e32 v1, v1, v1
	v_max_f32_e32 v1, v2, v1
	v_xor_b32_e32 v2, 2, v206
	v_cmp_lt_i32_e32 vcc, v2, v89
	v_max_f32_e32 v0, v0, v3
	s_addc_u32 s1, s8, s13
	v_cndmask_b32_e32 v2, v206, v2, vcc
	v_lshlrev_b32_e32 v2, 2, v2
	ds_bpermute_b32 v3, v2, v0
	ds_bpermute_b32 v2, v2, v1
	s_lshl_b64 s[4:5], s[46:47], 1
	v_add_u32_e32 v24, 32, v22
	s_add_u32 s0, s0, s4
	s_waitcnt lgkmcnt(1)
	v_max_f32_e32 v3, v3, v3
	s_waitcnt lgkmcnt(0)
	v_max_f32_e32 v2, v2, v2
	v_max_f32_e32 v1, v1, v2
	v_xor_b32_e32 v2, 4, v206
	v_cmp_lt_i32_e32 vcc, v2, v89
	v_max_f32_e32 v0, v0, v3
	v_mad_i64_i32 v[4:5], s[6:7], v24, s11, 0
	v_cndmask_b32_e32 v2, v206, v2, vcc
	v_lshlrev_b32_e32 v2, 2, v2
	ds_bpermute_b32 v3, v2, v0
	ds_bpermute_b32 v2, v2, v1
	s_addc_u32 s1, s1, s5
	v_lshlrev_b64 v[168:169], 1, v[4:5]
	v_lshl_add_u64 v[4:5], s[0:1], 0, v[168:169]
	s_waitcnt lgkmcnt(1)
	v_max_f32_e32 v3, v3, v3
	s_waitcnt lgkmcnt(0)
	v_max_f32_e32 v2, v2, v2
	v_max_f32_e32 v1, v1, v2
	v_xor_b32_e32 v2, 8, v206
	v_cmp_lt_i32_e32 vcc, v2, v89
	v_max_f32_e32 v0, v0, v3
	v_and_b32_e32 v23, 15, v162
	v_cndmask_b32_e32 v2, v206, v2, vcc
	v_lshlrev_b32_e32 v2, 2, v2
	ds_bpermute_b32 v3, v2, v0
	ds_bpermute_b32 v2, v2, v1
	v_lshlrev_b32_e32 v166, 4, v23
	v_mov_b32_e32 v167, v181
	v_lshl_add_u64 v[4:5], v[4:5], 0, v[166:167]
	s_waitcnt lgkmcnt(1)
	v_max_f32_e32 v3, v3, v3
	s_waitcnt lgkmcnt(0)
	v_max_f32_e32 v2, v2, v2
	v_max_f32_e32 v1, v1, v2
	v_xor_b32_e32 v2, 16, v206
	v_cmp_lt_i32_e32 vcc, v2, v89
	v_max_f32_e32 v0, v0, v3
	s_nop 0
	v_cndmask_b32_e32 v2, v206, v2, vcc
	v_lshlrev_b32_e32 v2, 2, v2
	ds_bpermute_b32 v3, v2, v0
	v_cmp_gt_i32_e64 s[40:41], 64, v162
	s_waitcnt lgkmcnt(0)
	v_max_f32_e32 v3, v3, v3
	v_max_f32_e32 v19, v0, v3
	ds_bpermute_b32 v0, v2, v1
	ds_bpermute_b32 v21, v170, v19
	s_waitcnt lgkmcnt(1)
	v_max_f32_e32 v0, v0, v0
	v_max_f32_e32 v18, v1, v0
	v_mad_i64_i32 v[0:1], s[6:7], v22, s11, 0
	v_lshlrev_b64 v[164:165], 1, v[0:1]
	v_lshl_add_u64 v[0:1], s[0:1], 0, v[164:165]
	s_add_u32 s0, s9, s15
	s_addc_u32 s1, s10, s13
	s_add_u32 s0, s0, s4
	s_addc_u32 s1, s1, s5
	v_lshl_add_u64 v[8:9], s[0:1], 0, v[164:165]
	v_lshl_add_u64 v[12:13], s[0:1], 0, v[168:169]
	v_lshl_add_u64 v[0:1], v[0:1], 0, v[166:167]
	v_lshl_add_u64 v[8:9], v[8:9], 0, v[166:167]
	v_lshl_add_u64 v[12:13], v[12:13], 0, v[166:167]
	s_nop 0
	ds_bpermute_b32 v20, v170, v18
	s_nop 0
	s_nop 0
	s_nop 0
	s_and_saveexec_b64 s[0:1], s[40:41]
	s_cbranch_execz .LBB0_775
	v_add_u32_e32 v26, s42, v162
	v_ashrrev_i32_e32 v27, 31, v26
	v_lshl_add_u64 v[26:27], v[26:27], 2, s[54:55]
	global_load_dword v173, v[26:27], off
.LBB0_775:
	s_or_b64 exec, exec, s[0:1]
	s_movk_i32 s0, 0x110
	v_mul_lo_u32 v167, v22, s0
	v_add3_u32 v26, 0, v167, v166
	s_waitcnt vmcnt(2)
	ds_write_b128 v26, v[186:189]
	ds_write_b128 v26, v[190:193] offset:8704
	v_mad_u64_u32 v[0:1], s[0:1], v22, 48, v[26:27]
	s_waitcnt vmcnt(1)
	ds_write_b128 v0, v[194:197] offset:34816
	v_mul_lo_u32 v0, v24, 48
	s_movk_i32 s0, 0x2200
	v_add3_u32 v0, v26, s0, v0
	s_waitcnt vmcnt(0)
	ds_write_b128 v0, v[198:201] offset:34816
	v_lshlrev_b32_e32 v171, 2, v171
	v_add_u32_e32 v171, 0x12a00, v171
	s_and_saveexec_b64 s[0:1], s[40:41]
	v_lshl_add_u32 v0, v162, 2, 0
	v_add_u32_e32 v0, 0x12800, v0
	v_lshlrev_b32_e32 v173, 2, v173
	ds_write_b32 v0, v173
	s_or_b64 exec, exec, s[0:1]
	s_or_b32 s0, s42, 64
	s_mul_i32 s7, s0, 0x1800
	s_mul_hi_i32 s6, s0, 0x1800
	s_add_u32 s0, s95, s7
	s_addc_u32 s1, s8, s6
	s_add_u32 s0, s0, s4
	v_lshlrev_b32_e32 v2, 3, v23
	s_addc_u32 s1, s1, s5
	v_lshl_add_u64 v[0:1], s[0:1], 0, v[164:165]
	v_lshlrev_b32_e32 v180, 1, v2
	v_lshl_add_u64 v[2:3], s[0:1], 0, v[168:169]
	s_add_u32 s0, s9, s7
	s_addc_u32 s1, s10, s6
	s_add_u32 s0, s0, s4
	v_lshl_add_u64 v[0:1], v[0:1], 0, v[180:181]
	s_addc_u32 s1, s1, s5
	v_lshl_add_u64 v[2:3], v[2:3], 0, v[180:181]
	global_load_dwordx4 v[144:147], v[0:1], off
	global_load_dwordx4 v[148:151], v[2:3], off
	v_lshl_add_u64 v[0:1], s[0:1], 0, v[164:165]
	v_lshl_add_u64 v[0:1], v[0:1], 0, v[180:181]
	v_lshl_add_u64 v[2:3], s[0:1], 0, v[168:169]
	v_lshl_add_u64 v[2:3], v[2:3], 0, v[180:181]
	global_load_dwordx4 v[152:155], v[0:1], off
	global_load_dwordx4 v[156:159], v[2:3], off
	s_and_saveexec_b64 s[0:1], s[40:41]
	s_cbranch_execz .LBB0_779
	s_ashr_i32 s43, s42, 31
	v_lshl_add_u64 v[0:1], s[42:43], 0, v[162:163]
	v_lshl_add_u64 v[0:1], v[0:1], 2, s[54:55]
	global_load_dword v173, v[0:1], off offset:256
